# attention: s_setprio 1 for waves 4-7 (s2) on top of hand-scheduled S2
# speedup vs baseline: 1.0055x; 1.0055x over previous
; #define LOADV(dst, ks_) do { _Pragma("unroll") for (int dvb = 0; dvb < 4; ++dvb) { dst[2 * dvb] = vtr(vp + dvb * 4096 + (ks_) * 1024); dst[2 * dvb + 1] = vtr(vp + dvb * 4096 + (ks_) * 1024 + 512); } } while (0)
; #define MF4(src, pfrag) do { _Pragma("unroll") for (int dvb = 0; dvb < 4; ++dvb) { \
;         const bf16x8 vf_ = __builtin_shufflevector(src[2 * dvb], src[2 * dvb + 1], 0, 1, 2, 3, 4, 5, 6, 7); o[dvb] = MFMA32(vf_, pfrag, o[dvb]); } } while (0)
; #define EXPQ(S, lo_, RS, PF) do { _Pragma("unroll") for (int i = lo_; i < lo_ + 8; ++i) { S[i] = ex2(S[i]); RS += S[i]; } \
;               u32x4 w_; w_.x = pk2(S[lo_], S[lo_ + 1]); w_.y = pk2(S[lo_ + 2], S[lo_ + 3]); w_.z = pk2(S[lo_ + 4], S[lo_ + 5]); w_.w = pk2(S[lo_ + 6], S[lo_ + 7]); PF = __builtin_bit_cast(bf16x8, w_); } while (0)
; DI void attn_unit(const Params& p, int bh, int qb, char* lds, float lam, int tid, int lane, int wid, const bool build_tab) {
;     ...
;             float rs0 = 0.f, rs1 = 0.f;
;     ...
;             EXPQ(s0, 0, rs0, pf[0]);
;             LOADV(vb, 1);
;             MF4(va, pf[0]);
;             EXPQ(s0, 8, rs1, pf[1]);
;             LOADV(va, 2);
;             MF4(vb, pf[1]);
;             EXPQ(s1, 0, rs0, pf[2]);
;             LOADV(vb, 3);
;             MF4(va, pf[2]);
;             EXPQ(s1, 8, rs1, pf[3]);
;             MF4(vb, pf[3]);
;             l += rs0 + rs1;
.LBB0_359:
	s_cmp_lt_u32 s59, 64
	s_cbranch_scc1 .Lp2_1
	s_setprio 1
.Lp2_1:
	ds_read_b64_tr_b16 v[242:243], v220 offset:21504
	ds_read_b64_tr_b16 v[244:245], v220 offset:22016
	ds_read_b64_tr_b16 v[246:247], v220 offset:25600
	ds_read_b64_tr_b16 v[248:249], v220 offset:26112
	v_exp_f32_e32 v222, v96
	v_exp_f32_e32 v224, v97
	v_exp_f32_e32 v226, v98
	v_exp_f32_e32 v228, v99
	v_exp_f32_e32 v230, v100
	v_exp_f32_e32 v232, v101
	v_exp_f32_e32 v234, v102
	v_exp_f32_e32 v236, v103
	v_cvt_pk_bf16_f32 v96, v222, v224
	v_cvt_pk_bf16_f32 v97, v226, v228
	v_cvt_pk_bf16_f32 v98, v230, v232
	v_cvt_pk_bf16_f32 v99, v234, v236
	ds_read_b64_tr_b16 v[100:101], v220 offset:17408
	ds_read_b64_tr_b16 v[102:103], v220 offset:17920
	s_waitcnt lgkmcnt(12)
	v_mfma_f32_32x32x16_bf16 v[48:63], v[140:143], v[96:99], v[48:63]
	ds_read_b64_tr_b16 v[250:251], v220 offset:29696
	ds_read_b64_tr_b16 v[252:253], v220 offset:30208
	v_exp_f32_e32 v223, v104
	v_exp_f32_e32 v225, v105
	v_exp_f32_e32 v227, v106
	v_add_f32_e32 v221, v224, v222
	s_waitcnt lgkmcnt(12)
	v_mfma_f32_32x32x16_bf16 v[32:47], v[136:139], v[96:99], v[32:47]
	v_exp_f32_e32 v229, v107
	v_exp_f32_e32 v231, v108
	v_exp_f32_e32 v233, v109
	v_add_f32_e32 v221, v226, v221
	s_waitcnt lgkmcnt(10)
	v_mfma_f32_32x32x16_bf16 v[16:31], v[132:135], v[96:99], v[16:31]
	v_exp_f32_e32 v235, v110
	v_exp_f32_e32 v237, v111
	v_add_f32_e32 v221, v228, v221
	v_add_f32_e32 v221, v230, v221
	ds_read_b64_tr_b16 v[104:105], v220 offset:18432
	ds_read_b64_tr_b16 v[106:107], v220 offset:18944
	ds_read_b64_tr_b16 v[108:109], v220 offset:19456
	ds_read_b64_tr_b16 v[110:111], v220 offset:19968
	s_waitcnt lgkmcnt(12)
	v_mfma_f32_32x32x16_bf16 v[0:15], v[128:131], v[96:99], v[0:15]
	ds_read_b64_tr_b16 v[128:129], v220 offset:26624
	ds_read_b64_tr_b16 v[130:131], v220 offset:27136
	v_cvt_pk_bf16_f32 v96, v223, v225
	v_cvt_pk_bf16_f32 v97, v227, v229
	v_cvt_pk_bf16_f32 v98, v231, v233
	v_cvt_pk_bf16_f32 v99, v235, v237
	v_exp_f32_e32 v140, v84
	v_exp_f32_e32 v142, v85
	s_waitcnt lgkmcnt(8)
	v_mfma_f32_32x32x16_bf16 v[48:63], v[100:103], v[96:99], v[48:63]
	v_exp_f32_e32 v238, v86
	v_exp_f32_e32 v240, v87
	v_add_f32_e32 v221, v232, v221
	ds_read_b64_tr_b16 v[84:85], v220 offset:22528
	ds_read_b64_tr_b16 v[86:87], v220 offset:23040
	v_exp_f32_e32 v136, v82
	s_waitcnt lgkmcnt(14)
	v_mfma_f32_32x32x16_bf16 v[32:47], v[242:245], v[96:99], v[32:47]
	ds_read_b64_tr_b16 v[242:243], v220 offset:23552
	ds_read_b64_tr_b16 v[244:245], v220 offset:24064
	v_exp_f32_e32 v138, v83
	v_exp_f32_e32 v132, v80
	v_exp_f32_e32 v134, v81
	v_add_f32_e32 v221, v234, v221
	s_waitcnt lgkmcnt(14)
	v_mfma_f32_32x32x16_bf16 v[16:31], v[246:249], v[96:99], v[16:31]
	ds_read_b64_tr_b16 v[246:247], v220 offset:27648
	ds_read_b64_tr_b16 v[248:249], v220 offset:28160
	v_cvt_pk_bf16_f32 v80, v132, v134
	v_cvt_pk_bf16_f32 v81, v136, v138
	v_cvt_pk_bf16_f32 v82, v140, v142
	v_cvt_pk_bf16_f32 v83, v238, v240
	v_exp_f32_e32 v133, v88
	v_exp_f32_e32 v135, v89
	s_waitcnt lgkmcnt(12)
	v_mfma_f32_32x32x16_bf16 v[0:15], v[250:253], v[96:99], v[0:15]
	ds_read_b64_tr_b16 v[250:251], v220 offset:31744
	ds_read_b64_tr_b16 v[252:253], v220 offset:32256
	v_exp_f32_e32 v137, v90
	v_exp_f32_e32 v139, v91
	v_add_f32_e32 v221, v236, v221
	ds_read_b64_tr_b16 v[88:89], v220 offset:30720
	ds_read_b64_tr_b16 v[90:91], v220 offset:31232
	v_exp_f32_e32 v141, v92
	s_waitcnt lgkmcnt(14)
	v_mfma_f32_32x32x16_bf16 v[48:63], v[104:107], v[80:83], v[48:63]
	v_exp_f32_e32 v143, v93
	v_exp_f32_e32 v239, v94
	v_exp_f32_e32 v241, v95
	v_add_f32_e32 v221, v132, v221
	s_waitcnt lgkmcnt(8)
	v_mfma_f32_32x32x16_bf16 v[32:47], v[84:87], v[80:83], v[32:47]
	v_add_f32_e32 v93, v225, v223
	v_add_f32_e32 v221, v134, v221
	v_add_f32_e32 v93, v227, v93
	v_add_f32_e32 v221, v136, v221
	v_add_f32_e32 v93, v229, v93
	v_add_f32_e32 v221, v138, v221
	s_waitcnt lgkmcnt(10)
	v_mfma_f32_32x32x16_bf16 v[16:31], v[128:131], v[80:83], v[16:31]
	v_add_f32_e32 v93, v231, v93
	v_add_f32_e32 v221, v140, v221
	v_add_f32_e32 v93, v233, v93
	v_add_f32_e32 v221, v142, v221
	v_add_f32_e32 v93, v235, v93
	v_add_f32_e32 v221, v238, v221
	v_add_f32_e32 v93, v237, v93
	s_waitcnt lgkmcnt(0)
	v_mfma_f32_32x32x16_bf16 v[0:15], v[88:91], v[80:83], v[0:15]
	v_cvt_pk_bf16_f32 v80, v133, v135
	v_cvt_pk_bf16_f32 v81, v137, v139
	v_cvt_pk_bf16_f32 v82, v141, v143
	v_cvt_pk_bf16_f32 v83, v239, v241
	v_add_f32_e32 v221, v240, v221
	v_add_f32_e32 v93, v133, v93
	s_waitcnt lgkmcnt(12)
	v_mfma_f32_32x32x16_bf16 v[48:63], v[108:111], v[80:83], v[48:63]
	v_add_f32_e32 v93, v135, v93
	v_add_f32_e32 v93, v137, v93
	s_waitcnt lgkmcnt(6)
	v_mfma_f32_32x32x16_bf16 v[32:47], v[242:245], v[80:83], v[32:47]
	v_add_f32_e32 v93, v139, v93
	v_add_f32_e32 v93, v141, v93
	s_waitcnt lgkmcnt(4)
	v_mfma_f32_32x32x16_bf16 v[16:31], v[246:249], v[80:83], v[16:31]
	v_add_f32_e32 v93, v143, v93
	v_add_f32_e32 v93, v239, v93
	s_waitcnt lgkmcnt(2)
	v_mfma_f32_32x32x16_bf16 v[0:15], v[250:253], v[80:83], v[0:15]
	v_add_f32_e32 v93, v241, v93
	v_add_f32_e32 v221, v221, v93
	v_add_f32_e32 v146, v146, v221
	s_setprio 0

; #define LOADV(dst, ks_) do { _Pragma("unroll") for (int dvb = 0; dvb < 4; ++dvb) { dst[2 * dvb] = vtr(vp + dvb * 4096 + (ks_) * 1024); dst[2 * dvb + 1] = vtr(vp + dvb * 4096 + (ks_) * 1024 + 512); } } while (0)
; #define MF4(src, pfrag) do { _Pragma("unroll") for (int dvb = 0; dvb < 4; ++dvb) { \
;         const bf16x8 vf_ = __builtin_shufflevector(src[2 * dvb], src[2 * dvb + 1], 0, 1, 2, 3, 4, 5, 6, 7); o[dvb] = MFMA32(vf_, pfrag, o[dvb]); } } while (0)
; #define EXPQ(S, lo_, RS, PF) do { _Pragma("unroll") for (int i = lo_; i < lo_ + 8; ++i) { S[i] = ex2(S[i]); RS += S[i]; } \
;               u32x4 w_; w_.x = pk2(S[lo_], S[lo_ + 1]); w_.y = pk2(S[lo_ + 2], S[lo_ + 3]); w_.z = pk2(S[lo_ + 4], S[lo_ + 5]); w_.w = pk2(S[lo_ + 6], S[lo_ + 7]); PF = __builtin_bit_cast(bf16x8, w_); } while (0)
; DI void attn_unit(const Params& p, int bh, int qb, char* lds, float lam, int tid, int lane, int wid, const bool build_tab) {
;     ...
;             float rs0 = 0.f, rs1 = 0.f;
;     ...
;             EXPQ(s0, 0, rs0, pf[0]);
;             LOADV(vb, 1);
;             MF4(va, pf[0]);
;             EXPQ(s0, 8, rs1, pf[1]);
;             LOADV(va, 2);
;             MF4(vb, pf[1]);
;             EXPQ(s1, 0, rs0, pf[2]);
;             LOADV(vb, 3);
;             MF4(va, pf[2]);
;             EXPQ(s1, 8, rs1, pf[3]);
;             MF4(vb, pf[3]);
;             l += rs0 + rs1;
.Lp2_0:
	ds_read_b64_tr_b16 v[230:231], v177 offset:21504
	ds_read_b64_tr_b16 v[232:233], v177 offset:22016
	ds_read_b64_tr_b16 v[234:235], v177 offset:25600
	ds_read_b64_tr_b16 v[236:237], v177 offset:26112
	v_exp_f32_e32 v178, v96
	v_exp_f32_e32 v180, v97
	v_exp_f32_e32 v182, v98
	v_exp_f32_e32 v184, v99
	v_exp_f32_e32 v186, v100
	v_exp_f32_e32 v188, v101
	v_exp_f32_e32 v190, v102
	v_exp_f32_e32 v192, v103
	v_cvt_pk_bf16_f32 v96, v178, v180
	v_cvt_pk_bf16_f32 v97, v182, v184
	v_cvt_pk_bf16_f32 v98, v186, v188
	v_cvt_pk_bf16_f32 v99, v190, v192
	ds_read_b64_tr_b16 v[100:101], v177 offset:17408
	ds_read_b64_tr_b16 v[102:103], v177 offset:17920
	s_waitcnt lgkmcnt(12)
	v_mfma_f32_32x32x16_bf16 v[48:63], v[140:143], v[96:99], v[48:63]
	ds_read_b64_tr_b16 v[238:239], v177 offset:29696
	ds_read_b64_tr_b16 v[240:241], v177 offset:30208
	v_exp_f32_e32 v179, v104
	v_exp_f32_e32 v181, v105
	v_exp_f32_e32 v183, v106
	v_add_f32_e32 v242, v180, v178
	s_waitcnt lgkmcnt(12)
	v_mfma_f32_32x32x16_bf16 v[32:47], v[136:139], v[96:99], v[32:47]
	v_exp_f32_e32 v185, v107
	v_exp_f32_e32 v187, v108
	v_exp_f32_e32 v189, v109
	v_add_f32_e32 v242, v182, v242
	s_waitcnt lgkmcnt(10)
	v_mfma_f32_32x32x16_bf16 v[16:31], v[132:135], v[96:99], v[16:31]
	v_exp_f32_e32 v191, v110
	v_exp_f32_e32 v193, v111
	v_add_f32_e32 v242, v184, v242
	v_add_f32_e32 v242, v186, v242
	ds_read_b64_tr_b16 v[104:105], v177 offset:18432
	ds_read_b64_tr_b16 v[106:107], v177 offset:18944
	ds_read_b64_tr_b16 v[108:109], v177 offset:19456
	ds_read_b64_tr_b16 v[110:111], v177 offset:19968
	s_waitcnt lgkmcnt(12)
	v_mfma_f32_32x32x16_bf16 v[0:15], v[128:131], v[96:99], v[0:15]
	ds_read_b64_tr_b16 v[128:129], v177 offset:26624
	ds_read_b64_tr_b16 v[130:131], v177 offset:27136
	v_cvt_pk_bf16_f32 v96, v179, v181
	v_cvt_pk_bf16_f32 v97, v183, v185
	v_cvt_pk_bf16_f32 v98, v187, v189
	v_cvt_pk_bf16_f32 v99, v191, v193
	v_exp_f32_e32 v140, v84
	v_exp_f32_e32 v142, v85
	s_waitcnt lgkmcnt(8)
	v_mfma_f32_32x32x16_bf16 v[48:63], v[100:103], v[96:99], v[48:63]
	v_exp_f32_e32 v194, v86
	v_exp_f32_e32 v196, v87
	v_add_f32_e32 v242, v188, v242
	ds_read_b64_tr_b16 v[84:85], v177 offset:22528
	ds_read_b64_tr_b16 v[86:87], v177 offset:23040
	v_exp_f32_e32 v136, v82
	s_waitcnt lgkmcnt(14)
	v_mfma_f32_32x32x16_bf16 v[32:47], v[230:233], v[96:99], v[32:47]
	ds_read_b64_tr_b16 v[230:231], v177 offset:23552
	ds_read_b64_tr_b16 v[232:233], v177 offset:24064
	v_exp_f32_e32 v138, v83
	v_exp_f32_e32 v132, v80
	v_exp_f32_e32 v134, v81
	v_add_f32_e32 v242, v190, v242
	s_waitcnt lgkmcnt(14)
	v_mfma_f32_32x32x16_bf16 v[16:31], v[234:237], v[96:99], v[16:31]
	ds_read_b64_tr_b16 v[234:235], v177 offset:27648
	ds_read_b64_tr_b16 v[236:237], v177 offset:28160
	v_cvt_pk_bf16_f32 v80, v132, v134
	v_cvt_pk_bf16_f32 v81, v136, v138
	v_cvt_pk_bf16_f32 v82, v140, v142
	v_cvt_pk_bf16_f32 v83, v194, v196
	v_exp_f32_e32 v133, v88
	v_exp_f32_e32 v135, v89
	s_waitcnt lgkmcnt(12)
	v_mfma_f32_32x32x16_bf16 v[0:15], v[238:241], v[96:99], v[0:15]
	ds_read_b64_tr_b16 v[238:239], v177 offset:31744
	ds_read_b64_tr_b16 v[240:241], v177 offset:32256
	v_exp_f32_e32 v137, v90
	v_exp_f32_e32 v139, v91
	v_add_f32_e32 v242, v192, v242
	ds_read_b64_tr_b16 v[88:89], v177 offset:30720
	ds_read_b64_tr_b16 v[90:91], v177 offset:31232
	v_exp_f32_e32 v141, v92
	s_waitcnt lgkmcnt(14)
	v_mfma_f32_32x32x16_bf16 v[48:63], v[104:107], v[80:83], v[48:63]
	v_exp_f32_e32 v143, v93
	v_exp_f32_e32 v195, v94
	v_exp_f32_e32 v197, v95
	v_add_f32_e32 v242, v132, v242
	s_waitcnt lgkmcnt(8)
	v_mfma_f32_32x32x16_bf16 v[32:47], v[84:87], v[80:83], v[32:47]
	v_add_f32_e32 v243, v181, v179
	v_add_f32_e32 v242, v134, v242
	v_add_f32_e32 v243, v183, v243
	v_add_f32_e32 v242, v136, v242
	v_add_f32_e32 v243, v185, v243
	v_add_f32_e32 v242, v138, v242
	s_waitcnt lgkmcnt(10)
	v_mfma_f32_32x32x16_bf16 v[16:31], v[128:131], v[80:83], v[16:31]
	v_add_f32_e32 v243, v187, v243
	v_add_f32_e32 v242, v140, v242
	v_add_f32_e32 v243, v189, v243
	v_add_f32_e32 v242, v142, v242
	v_add_f32_e32 v243, v191, v243
	v_add_f32_e32 v242, v194, v242
	v_add_f32_e32 v243, v193, v243
	s_waitcnt lgkmcnt(0)
	v_mfma_f32_32x32x16_bf16 v[0:15], v[88:91], v[80:83], v[0:15]
	v_cvt_pk_bf16_f32 v80, v133, v135
	v_cvt_pk_bf16_f32 v81, v137, v139
	v_cvt_pk_bf16_f32 v82, v141, v143
	v_cvt_pk_bf16_f32 v83, v195, v197
	v_add_f32_e32 v242, v196, v242
	v_add_f32_e32 v243, v133, v243
	s_waitcnt lgkmcnt(12)
	v_mfma_f32_32x32x16_bf16 v[48:63], v[108:111], v[80:83], v[48:63]
	v_add_f32_e32 v243, v135, v243
	v_add_f32_e32 v243, v137, v243
	s_waitcnt lgkmcnt(6)
	v_mfma_f32_32x32x16_bf16 v[32:47], v[230:233], v[80:83], v[32:47]
	v_add_f32_e32 v243, v139, v243
	v_add_f32_e32 v243, v141, v243
	s_waitcnt lgkmcnt(4)
	v_mfma_f32_32x32x16_bf16 v[16:31], v[234:237], v[80:83], v[16:31]
	v_add_f32_e32 v243, v143, v243
	v_add_f32_e32 v243, v195, v243
	s_waitcnt lgkmcnt(2)
	v_mfma_f32_32x32x16_bf16 v[0:15], v[238:241], v[80:83], v[0:15]
	v_add_f32_e32 v243, v197, v243
	v_add_f32_e32 v242, v242, v243
	v_add_f32_e32 v176, v176, v242
	s_setprio 0
